# GEMM pipeline fill: second batch of 6 LDS-DMA issues moved ahead of the first wait+barrier (vmcnt 2 -> 8) in all six GEMM calls so the two prologue latencies overlap
# speedup vs baseline: 1.0117x; 1.0066x over previous
; #define PG8_STAGE(bufoff, gbase, voff) do { _Pragma("unroll") for (int _i = 0; _i < 2; ++_i) \
;         __builtin_amdgcn_global_load_lds((const unsigned*)((const char*)(gbase) + (voff)[_i]), (PG8_LAS unsigned*)(lds + (bufoff) + ldsw + _i * 8192), 16, 0, 0); } while (0)
; #define PG8_WAIT_V(n) asm volatile("s_waitcnt vmcnt(" #n ")" ::: "memory")
; #define PG8_BAR __builtin_amdgcn_s_barrier()
; template <class Epi, class Sched, bool ALIGN_EPI = false, bool SP2 = false>
; __device__ __forceinline__ void gemm_phase(PG8_LAS unsigned char* lds, const Gemm g, const Sched& S, const Epi& E) {
;     ...
;     for (int i = 0; i < 2; ++i) { int R, C; stage_rc(tid * 16 + i * 8192, R, C); const int Rb = Epi::PERM ? ((R & ~31) + perm32(R & 31)) : R;
;         voffA[i] = (unsigned)(R * g.lda + C) * 2u; voffB[i] = (unsigned)(Rb * K + C) * 2u; }
;     const size_t kstep = (size_t)(BK * 2);
;     const size_t hstepA = (size_t)HALF * g.lda * 2, hstepB = (size_t)HALF * K * 2;
;     const size_t tstepA = 2 * hstepA, tstepB = 2 * hstepB;
;     const unsigned ldsw = (unsigned)wid * 1024u;
;     const int aoff = lds_byte(wr * 64 + fr, fq * 8), boff = lds_byte(wc * 32 + fr, fq * 8);
;     ...
;     if constexpr (SP2) {
;         PG8_STAGE(PG8_SB(0, 0), cB, voffB); PG8_STAGE(PG8_SB(0, 1), cB + hstepB, voffB); PG8_STAGE(PG8_SA(0, 0), cA, voffA); PG8_STAGE(PG8_SA(0, 1), cA + hstepA, voffA);
;         if (wr == 1) PG8_BAR;
;         PG8_WAIT_V(2); PG8_BAR;
;         PG8_STAGE(PG8_SB(1, 0), cB + kstep, voffB); PG8_STAGE(PG8_SA(1, 0), cA + kstep, voffA); PG8_STAGE(PG8_SB(1, 1), cB + hstepB + kstep, voffB);
;         PG8_WAIT_V(6); PG8_BAR;
.LBB0_116:
	s_add_u32 s43, s88, 0x6000000
	s_addc_u32 s44, s89, 0
	s_add_u32 s45, s88, 0x16000000
	s_addc_u32 s46, s89, 0
	s_lshl_b32 s1, s1, 5
	s_mov_b64 s[14:15], 0x80
	s_and_b32 s1, s1, 0x60
	s_add_i32 m0, s39, 0x18000
	v_lshl_add_u64 v[6:7], v[6:7], 0, s[14:15]
	s_lshl_b32 s3, s0, 13
	s_lshl_b32 s5, s1, 7
	global_load_lds_dwordx4 v[6:7], off
	v_lshl_add_u64 v[4:5], v[4:5], 0, s[14:15]
	s_add_i32 m0, s39, 0x1a000
	s_add_i32 s47, s39, 0x8000
	s_add_i32 s48, s39, 0xa000
	global_load_lds_dwordx4 v[4:5], off
	v_lshl_add_u64 v[0:1], v[0:1], 0, s[14:15]
	s_mov_b32 m0, s47
	s_add_u32 s16, s26, 0x80080
	global_load_lds_dwordx4 v[0:1], off
	v_lshl_add_u64 v[0:1], v[2:3], 0, s[14:15]
	s_mov_b32 m0, s48
	s_addc_u32 s17, s27, 0
	global_load_lds_dwordx4 v[0:1], off
	s_add_i32 m0, s39, 0x1c000
	v_lshl_add_u64 v[0:1], s[16:17], 0, v[130:131]
	global_load_lds_dwordx4 v[0:1], off
	v_lshl_add_u64 v[0:1], s[16:17], 0, v[134:135]
	s_add_i32 m0, s39, 0x1e000
	v_lshlrev_b32_e32 v2, 2, v157
	global_load_lds_dwordx4 v[0:1], off
	s_waitcnt vmcnt(8)
	s_barrier
	v_and_b32_e32 v0, 15, v157
	v_lshl_or_b32 v158, s0, 6, v0
	v_lshlrev_b32_e32 v1, 1, v11
	v_lshlrev_b32_e32 v3, 6, v157
	s_movk_i32 s0, 0x3c0
	v_lshl_or_b32 v0, v0, 6, v1
	v_and_b32_e32 v2, 32, v2
	v_and_or_b32 v1, v3, s0, v1
	v_bitop3_b32 v159, s5, v1, v2 bitop3:0xf6
	v_lshlrev_b32_e32 v1, 10, v157
	v_bitop3_b32 v0, v0, s3, v2 bitop3:0xde
	v_and_b32_e32 v1, 0xe0000, v1
	v_lshlrev_b32_e32 v2, 13, v10
	v_or3_b32 v1, v8, v1, v2
	v_add_u32_e32 v138, v1, v9
	v_lshlrev_b32_e32 v1, 6, v12
	s_waitcnt vmcnt(6)
	s_cmpk_lt_u32 s10, 0x100
	v_and_b32_e32 v1, 0x1e0000, v1
	s_cselect_b64 s[16:17], -1, 0
	v_readlane_b32 s0, v234, 2
	v_or3_b32 v1, v8, v1, v2
	s_add_i32 s54, 0, 0x10000
	s_add_i32 s55, 0, 0x14000
	s_ashr_i32 s49, s33, 31
	s_ashr_i32 s50, s0, 31
	v_or_b32_e32 v160, s1, v11
	v_mov_b32_e32 v139, v137
	v_add_u32_e32 v140, v1, v9
	v_mov_b32_e32 v141, v137
	v_mov_b64_e32 v[142:143], 0xe00
	v_mov_b64_e32 v[144:145], 0xdff
	s_movk_i32 s51, 0x1c1
	v_add_u32_e32 v161, s54, v159
	v_add_u32_e32 v162, s55, v159
	v_add_u32_e32 v163, 0, v0
	s_movk_i32 s56, 0x1000
	v_mov_b32_e32 v164, 0x3e0293ee
	s_mov_b32 s57, 0
	s_barrier
	s_branch .LBB0_119

; #define PG8_STAGE(bufoff, gbase, voff) do { _Pragma("unroll") for (int _i = 0; _i < 2; ++_i) \
;         __builtin_amdgcn_global_load_lds((const unsigned*)((const char*)(gbase) + (voff)[_i]), (PG8_LAS unsigned*)(lds + (bufoff) + ldsw + _i * 8192), 16, 0, 0); } while (0)
; #define PG8_WAIT_V(n) asm volatile("s_waitcnt vmcnt(" #n ")" ::: "memory")
; #define PG8_BAR __builtin_amdgcn_s_barrier()
; template <class Epi, class Sched, bool ALIGN_EPI = false, bool SP2 = false>
; __device__ __forceinline__ void gemm_phase(PG8_LAS unsigned char* lds, const Gemm g, const Sched& S, const Epi& E) {
;     ...
;     if constexpr (SP2) {
;         PG8_STAGE(PG8_SB(0, 0), cB, voffB); PG8_STAGE(PG8_SB(0, 1), cB + hstepB, voffB); PG8_STAGE(PG8_SA(0, 0), cA, voffA); PG8_STAGE(PG8_SA(0, 1), cA + hstepA, voffA);
;         if (wr == 1) PG8_BAR;
;         PG8_WAIT_V(2); PG8_BAR;
;         PG8_STAGE(PG8_SB(1, 0), cB + kstep, voffB); PG8_STAGE(PG8_SA(1, 0), cA + kstep, voffA); PG8_STAGE(PG8_SB(1, 1), cB + hstepB + kstep, voffB);
;         PG8_WAIT_V(6); PG8_BAR;
.LBB0_622:
	s_add_u32 s12, s88, 0x16000000
	s_addc_u32 s13, s89, 0
	s_lshl_b32 s14, s14, 5
	s_and_b32 s20, s14, 0x60
	s_mov_b64 s[14:15], 0x80
	s_add_i32 m0, s43, 0x18000
	v_lshl_add_u64 v[6:7], v[6:7], 0, s[14:15]
	s_lshl_b32 s17, s1, 13
	global_load_lds_dwordx4 v[6:7], off
	v_lshl_add_u64 v[2:3], v[2:3], 0, s[14:15]
	s_add_i32 m0, s43, 0x1a000
	s_add_i32 s60, s43, 0x8000
	s_add_i32 s61, s43, 0xa000
	global_load_lds_dwordx4 v[2:3], off
	v_lshl_add_u64 v[0:1], v[0:1], 0, s[14:15]
	s_mov_b32 m0, s60
	s_add_u32 s18, s46, 0x80080
	global_load_lds_dwordx4 v[0:1], off
	v_lshl_add_u64 v[0:1], v[4:5], 0, s[14:15]
	s_mov_b32 m0, s61
	s_addc_u32 s19, s47, 0
	global_load_lds_dwordx4 v[0:1], off
	s_add_i32 m0, s43, 0x1c000
	v_lshl_add_u64 v[0:1], s[18:19], 0, v[130:131]
	global_load_lds_dwordx4 v[0:1], off
	v_lshl_add_u64 v[0:1], s[18:19], 0, v[134:135]
	s_add_i32 m0, s43, 0x1e000
	v_lshlrev_b32_e32 v2, 13, v152
	global_load_lds_dwordx4 v[0:1], off
	s_waitcnt vmcnt(8)
	s_barrier
	v_lshlrev_b32_e32 v1, 2, v155
	v_lshl_or_b32 v0, v155, 6, v158
	v_and_b32_e32 v1, 32, v1
	v_bitop3_b32 v0, v0, s17, v1 bitop3:0xde
	v_lshlrev_b32_e32 v1, 10, v157
	v_and_b32_e32 v1, 0xe0000, v1
	v_or3_b32 v1, v150, v1, v2
	v_add_u32_e32 v136, v1, v151
	v_lshlrev_b32_e32 v1, 6, v154
	s_waitcnt vmcnt(6)
	s_cmpk_lt_u32 s16, 0x100
	v_and_b32_e32 v1, 0x1e0000, v1
	v_lshl_or_b32 v161, s20, 7, v159
	s_cselect_b64 s[16:17], -1, 0
	v_or3_b32 v1, v150, v1, v2
	s_add_i32 s63, 0, 0x10000
	s_add_i32 s64, 0, 0x14000
	s_sext_i32_i8 s65, s0
	v_lshl_or_b32 v160, s1, 6, v155
	s_ashr_i32 s62, s33, 31
	v_or_b32_e32 v162, s20, v153
	v_mov_b32_e32 v137, v131
	v_add_u32_e32 v138, v1, v151
	v_mov_b32_e32 v139, v131
	v_mov_b64_e32 v[140:141], 0x200
	v_mov_b64_e32 v[142:143], 0x1ff
	v_add_u32_e32 v163, s63, v161
	v_add_u32_e32 v164, s64, v161
	v_add_u32_e32 v165, 0, v0
	s_mov_b64 s[18:19], 0x80100
	s_mov_b64 s[20:21], 0x90000
	s_mov_b64 s[22:23], 0x90100
	s_mov_b64 s[24:25], 0xa0000
	s_mov_b64 s[26:27], 0xa0100
	s_mov_b64 s[28:29], 0xb0000
	s_mov_b64 s[30:31], 0xb0100
	s_barrier
	s_branch .LBB0_625

; #define PG8_STAGE(bufoff, gbase, voff) do { _Pragma("unroll") for (int _i = 0; _i < 2; ++_i) \
;         __builtin_amdgcn_global_load_lds((const unsigned*)((const char*)(gbase) + (voff)[_i]), (PG8_LAS unsigned*)(lds + (bufoff) + ldsw + _i * 8192), 16, 0, 0); } while (0)
; #define PG8_WAIT_V(n) asm volatile("s_waitcnt vmcnt(" #n ")" ::: "memory")
; #define PG8_BAR __builtin_amdgcn_s_barrier()
; template <class Epi, class Sched, bool ALIGN_EPI = false, bool SP2 = false>
; __device__ __forceinline__ void gemm_phase(PG8_LAS unsigned char* lds, const Gemm g, const Sched& S, const Epi& E) {
;     ...
;     if constexpr (SP2) {
;         PG8_STAGE(PG8_SB(0, 0), cB, voffB); PG8_STAGE(PG8_SB(0, 1), cB + hstepB, voffB); PG8_STAGE(PG8_SA(0, 0), cA, voffA); PG8_STAGE(PG8_SA(0, 1), cA + hstepA, voffA);
;         if (wr == 1) PG8_BAR;
;         PG8_WAIT_V(2); PG8_BAR;
;         PG8_STAGE(PG8_SB(1, 0), cB + kstep, voffB); PG8_STAGE(PG8_SA(1, 0), cA + kstep, voffA); PG8_STAGE(PG8_SB(1, 1), cB + hstepB + kstep, voffB);
;         PG8_WAIT_V(6); PG8_BAR;
.LBB0_646:
	s_add_u32 s12, s88, 0x1a000000
	s_addc_u32 s13, s89, 0
	s_lshl_b32 s14, s14, 5
	s_and_b32 s20, s14, 0x60
	s_mov_b64 s[14:15], 0x80
	s_add_i32 m0, s3, 0x18000
	v_lshl_add_u64 v[6:7], v[6:7], 0, s[14:15]
	s_lshl_b32 s17, s1, 13
	global_load_lds_dwordx4 v[6:7], off
	v_lshl_add_u64 v[2:3], v[2:3], 0, s[14:15]
	s_add_i32 m0, s3, 0x1a000
	s_add_i32 s58, s3, 0x8000
	s_add_i32 s59, s3, 0xa000
	global_load_lds_dwordx4 v[2:3], off
	v_lshl_add_u64 v[0:1], v[0:1], 0, s[14:15]
	s_mov_b32 m0, s58
	s_add_u32 s18, s44, 0x80080
	global_load_lds_dwordx4 v[0:1], off
	v_lshl_add_u64 v[0:1], v[4:5], 0, s[14:15]
	s_mov_b32 m0, s59
	s_addc_u32 s19, s45, 0
	global_load_lds_dwordx4 v[0:1], off
	s_add_i32 m0, s3, 0x1c000
	v_lshl_add_u64 v[0:1], s[18:19], 0, v[130:131]
	global_load_lds_dwordx4 v[0:1], off
	v_lshl_add_u64 v[0:1], s[18:19], 0, v[134:135]
	s_add_i32 m0, s3, 0x1e000
	v_lshlrev_b32_e32 v2, 13, v152
	global_load_lds_dwordx4 v[0:1], off
	s_waitcnt vmcnt(8)
	s_barrier
	v_lshlrev_b32_e32 v1, 2, v155
	v_lshl_or_b32 v0, v155, 6, v158
	v_and_b32_e32 v1, 32, v1
	v_bitop3_b32 v0, v0, s17, v1 bitop3:0xde
	v_lshlrev_b32_e32 v1, 10, v157
	v_and_b32_e32 v1, 0xe0000, v1
	v_or3_b32 v1, v150, v1, v2
	v_add_u32_e32 v136, v1, v151
	v_lshlrev_b32_e32 v1, 6, v154
	s_waitcnt vmcnt(6)
	s_cmpk_lt_u32 s16, 0x100
	v_and_b32_e32 v1, 0x1e0000, v1
	v_lshl_or_b32 v160, s1, 6, v155
	v_lshl_or_b32 v155, s20, 7, v159
	s_cselect_b64 s[16:17], -1, 0
	v_or3_b32 v1, v150, v1, v2
	s_add_i32 s61, 0, 0x10000
	s_add_i32 s62, 0, 0x14000
	s_sext_i32_i8 s63, s0
	s_ashr_i32 s60, s33, 31
	v_or_b32_e32 v153, s20, v153
	v_mov_b32_e32 v137, v131
	v_add_u32_e32 v138, v1, v151
	v_mov_b32_e32 v139, v131
	v_mov_b64_e32 v[140:141], 0x200
	v_mov_b64_e32 v[142:143], 0x1ff
	v_add_u32_e32 v150, s61, v155
	v_add_u32_e32 v151, s62, v155
	v_add_u32_e32 v152, 0, v0
	s_mov_b64 s[18:19], 0x80100
	s_mov_b64 s[20:21], 0x90000
	s_mov_b64 s[22:23], 0x90100
	s_mov_b64 s[24:25], 0xa0000
	s_mov_b64 s[26:27], 0xa0100
	s_mov_b64 s[28:29], 0xb0000
	s_mov_b64 s[30:31], 0xb0100
	s_barrier
	s_branch .LBB0_649

; #define PG8_STAGE(bufoff, gbase, voff) do { _Pragma("unroll") for (int _i = 0; _i < 2; ++_i) \
;         __builtin_amdgcn_global_load_lds((const unsigned*)((const char*)(gbase) + (voff)[_i]), (PG8_LAS unsigned*)(lds + (bufoff) + ldsw + _i * 8192), 16, 0, 0); } while (0)
; #define PG8_WAIT_V(n) asm volatile("s_waitcnt vmcnt(" #n ")" ::: "memory")
; #define PG8_BAR __builtin_amdgcn_s_barrier()
; template <class Epi, class Sched, bool ALIGN_EPI = false, bool SP2 = false>
; __device__ __forceinline__ void gemm_phase(PG8_LAS unsigned char* lds, const Gemm g, const Sched& S, const Epi& E) {
;     ...
;     if constexpr (SP2) {
;         PG8_STAGE(PG8_SB(0, 0), cB, voffB); PG8_STAGE(PG8_SB(0, 1), cB + hstepB, voffB); PG8_STAGE(PG8_SA(0, 0), cA, voffA); PG8_STAGE(PG8_SA(0, 1), cA + hstepA, voffA);
;         if (wr == 1) PG8_BAR;
;         PG8_WAIT_V(2); PG8_BAR;
;         PG8_STAGE(PG8_SB(1, 0), cB + kstep, voffB); PG8_STAGE(PG8_SA(1, 0), cA + kstep, voffA); PG8_STAGE(PG8_SB(1, 1), cB + hstepB + kstep, voffB);
;         PG8_WAIT_V(6); PG8_BAR;
.LBB0_723:
	s_add_u32 s10, s88, 0x2000000
	s_addc_u32 s11, s89, 0
	s_add_u32 s12, s88, 0x100000
	s_addc_u32 s13, s89, 0
	s_lshl_b32 s1, s1, 5
	s_mov_b64 s[14:15], 0x80
	s_and_b32 s5, s1, 0x60
	s_add_i32 m0, s27, 0x18000
	v_lshl_add_u64 v[6:7], v[6:7], 0, s[14:15]
	s_lshl_b32 s3, s0, 13
	s_lshl_b32 s1, s5, 7
	global_load_lds_dwordx4 v[6:7], off
	v_lshl_add_u64 v[4:5], v[4:5], 0, s[14:15]
	s_add_i32 m0, s27, 0x1a000
	s_add_i32 s45, s27, 0x8000
	s_add_i32 s46, s27, 0xa000
	global_load_lds_dwordx4 v[4:5], off
	v_lshl_add_u64 v[0:1], v[0:1], 0, s[14:15]
	s_mov_b32 m0, s45
	s_add_u32 s16, s30, 0x80080
	global_load_lds_dwordx4 v[0:1], off
	v_lshl_add_u64 v[0:1], v[2:3], 0, s[14:15]
	s_mov_b32 m0, s46
	s_addc_u32 s17, s31, 0
	global_load_lds_dwordx4 v[0:1], off
	s_add_i32 m0, s27, 0x1c000
	v_lshl_add_u64 v[0:1], s[16:17], 0, v[128:129]
	global_load_lds_dwordx4 v[0:1], off
	v_lshl_add_u64 v[0:1], s[16:17], 0, v[130:131]
	s_add_i32 m0, s27, 0x1e000
	v_lshlrev_b32_e32 v3, 2, v157
	global_load_lds_dwordx4 v[0:1], off
	s_waitcnt vmcnt(8)
	s_barrier
	v_and_b32_e32 v0, 15, v157
	v_bfe_u32 v1, v157, 4, 2
	v_lshl_or_b32 v146, s0, 6, v0
	v_lshlrev_b32_e32 v2, 4, v1
	v_lshlrev_b32_e32 v4, 6, v157
	s_movk_i32 s0, 0x3c0
	v_lshl_or_b32 v0, v0, 6, v2
	v_and_b32_e32 v3, 32, v3
	v_and_or_b32 v2, v4, s0, v2
	v_bitop3_b32 v147, s1, v2, v3 bitop3:0xf6
	v_cmp_eq_u32_e64 s[0:1], 0, v1
	v_lshl_or_b32 v148, v1, 2, s5
	v_lshlrev_b32_e32 v1, 9, v157
	v_and_b32_e32 v1, 0x70000, v1
	v_lshlrev_b32_e32 v2, 12, v10
	v_or3_b32 v1, v8, v1, v2
	v_add_u32_e32 v132, v1, v9
	v_lshlrev_b32_e32 v1, 5, v11
	v_bitop3_b32 v0, v0, s3, v3 bitop3:0xde
	s_waitcnt vmcnt(6)
	s_cmpk_lt_u32 s4, 0x100
	v_and_b32_e32 v1, 0xf0000, v1
	s_cselect_b64 s[16:17], -1, 0
	v_readlane_b32 s3, v234, 2
	v_or3_b32 v1, v8, v1, v2
	s_add_i32 s49, 0, 0x10000
	s_add_i32 s50, 0, 0x14000
	v_add_u32_e32 v151, 0, v0
	v_mbcnt_lo_u32_b32 v0, -1, 0
	s_ashr_i32 s47, s33, 31
	s_ashr_i32 s48, s3, 31
	v_mov_b32_e32 v133, v129
	v_add_u32_e32 v134, v1, v9
	v_mov_b32_e32 v135, v129
	v_mov_b64_e32 v[136:137], 0x200
	v_mov_b64_e32 v[138:139], 0x1ff
	v_add_u32_e32 v149, s49, v147
	v_add_u32_e32 v150, s50, v147
	v_mbcnt_hi_u32_b32 v152, -1, v0
	s_barrier
	s_branch .LBB0_726

; #define PG8_STAGE(bufoff, gbase, voff) do { _Pragma("unroll") for (int _i = 0; _i < 2; ++_i) \
;         __builtin_amdgcn_global_load_lds((const unsigned*)((const char*)(gbase) + (voff)[_i]), (PG8_LAS unsigned*)(lds + (bufoff) + ldsw + _i * 8192), 16, 0, 0); } while (0)
; #define PG8_WAIT_V(n) asm volatile("s_waitcnt vmcnt(" #n ")" ::: "memory")
; #define PG8_BAR __builtin_amdgcn_s_barrier()
; template <class Epi, class Sched, bool ALIGN_EPI = false, bool SP2 = false>
; __device__ __forceinline__ void gemm_phase(PG8_LAS unsigned char* lds, const Gemm g, const Sched& S, const Epi& E) {
;     ...
;     if constexpr (SP2) {
;         PG8_STAGE(PG8_SB(0, 0), cB, voffB); PG8_STAGE(PG8_SB(0, 1), cB + hstepB, voffB); PG8_STAGE(PG8_SA(0, 0), cA, voffA); PG8_STAGE(PG8_SA(0, 1), cA + hstepA, voffA);
;         if (wr == 1) PG8_BAR;
;         PG8_WAIT_V(2); PG8_BAR;
;         PG8_STAGE(PG8_SB(1, 0), cB + kstep, voffB); PG8_STAGE(PG8_SA(1, 0), cA + kstep, voffA); PG8_STAGE(PG8_SB(1, 1), cB + hstepB + kstep, voffB);
;         PG8_WAIT_V(6); PG8_BAR;
.LBB0_814:
	s_add_u32 s10, s88, 0x100000
	s_addc_u32 s11, s89, 0
	s_add_u32 s12, s88, 0xe000000
	s_addc_u32 s13, s89, 0
	s_lshl_b32 s14, s14, 5
	s_and_b32 s20, s14, 0x60
	s_mov_b64 s[14:15], 0x80
	s_add_i32 m0, s3, 0x18000
	v_lshl_add_u64 v[6:7], v[6:7], 0, s[14:15]
	s_lshl_b32 s17, s1, 13
	s_lshl_b32 s21, s20, 7
	global_load_lds_dwordx4 v[6:7], off
	v_lshl_add_u64 v[4:5], v[4:5], 0, s[14:15]
	s_add_i32 m0, s3, 0x1a000
	s_add_i32 s50, s3, 0x8000
	s_add_i32 s51, s3, 0xa000
	global_load_lds_dwordx4 v[4:5], off
	v_lshl_add_u64 v[0:1], v[0:1], 0, s[14:15]
	s_mov_b32 m0, s50
	s_add_u32 s18, s36, 0x80080
	global_load_lds_dwordx4 v[0:1], off
	v_lshl_add_u64 v[0:1], v[2:3], 0, s[14:15]
	s_mov_b32 m0, s51
	s_addc_u32 s19, s37, 0
	global_load_lds_dwordx4 v[0:1], off
	s_add_i32 m0, s3, 0x1c000
	v_lshl_add_u64 v[0:1], s[18:19], 0, v[130:131]
	global_load_lds_dwordx4 v[0:1], off
	v_lshl_add_u64 v[0:1], s[18:19], 0, v[134:135]
	s_add_i32 m0, s3, 0x1e000
	s_sext_i32_i16 s60, s0
	global_load_lds_dwordx4 v[0:1], off
	s_waitcnt vmcnt(8)
	s_barrier
	v_and_b32_e32 v0, 15, v157
	v_lshlrev_b32_e32 v1, 1, v11
	v_lshlrev_b32_e32 v2, 2, v157
	v_lshlrev_b32_e32 v3, 6, v157
	s_movk_i32 s0, 0x3c0
	v_lshl_or_b32 v152, s1, 6, v0
	v_lshl_or_b32 v0, v0, 6, v1
	v_and_b32_e32 v2, 32, v2
	v_and_or_b32 v1, v3, s0, v1
	v_bitop3_b32 v153, s21, v1, v2 bitop3:0xf6
	v_lshlrev_b32_e32 v1, 9, v157
	v_bitop3_b32 v0, v0, s17, v2 bitop3:0xde
	v_and_b32_e32 v1, 0x70000, v1
	v_lshlrev_b32_e32 v2, 12, v10
	v_or3_b32 v1, v8, v1, v2
	v_add_u32_e32 v136, v1, v9
	v_lshlrev_b32_e32 v1, 5, v12
	s_waitcnt vmcnt(6)
	s_cmpk_lt_u32 s16, 0x100
	v_and_b32_e32 v1, 0xf0000, v1
	s_cselect_b64 s[16:17], -1, 0
	v_or3_b32 v1, v8, v1, v2
	s_add_i32 s53, 0, 0x10000
	s_add_i32 s54, 0, 0x14000
	s_ashr_i32 s52, s33, 31
	v_or_b32_e32 v154, s20, v11
	v_mov_b32_e32 v137, v131
	v_add_u32_e32 v138, v1, v9
	v_mov_b32_e32 v139, v131
	v_mov_b64_e32 v[140:141], 0x800
	v_mov_b64_e32 v[142:143], 0x7ff
	v_add_u32_e32 v155, s53, v153
	v_add_u32_e32 v158, s54, v153
	v_add_u32_e32 v159, 0, v0
	v_mov_b32_e32 v160, 0x358637bd
	s_mov_b32 s55, 0xf800000
	v_mov_b32_e32 v161, 0x260
	s_mov_b64 s[18:19], 0x200000
	s_mov_b32 s56, 0x200000
	s_mov_b64 s[20:21], 0x240000
	s_mov_b32 s57, 0x240000
	s_mov_b64 s[22:23], 0x280000
	s_mov_b32 s58, 0x280000
	s_mov_b64 s[24:25], 0x2c0000
	s_mov_b32 s59, 0x2c0000
	s_barrier
	s_branch .LBB0_817

; #define PG8_STAGE(bufoff, gbase, voff) do { _Pragma("unroll") for (int _i = 0; _i < 2; ++_i) \
;         __builtin_amdgcn_global_load_lds((const unsigned*)((const char*)(gbase) + (voff)[_i]), (PG8_LAS unsigned*)(lds + (bufoff) + ldsw + _i * 8192), 16, 0, 0); } while (0)
; #define PG8_WAIT_V(n) asm volatile("s_waitcnt vmcnt(" #n ")" ::: "memory")
; #define PG8_BAR __builtin_amdgcn_s_barrier()
; template <class Epi, class Sched, bool ALIGN_EPI = false, bool SP2 = false>
; __device__ __forceinline__ void gemm_phase(PG8_LAS unsigned char* lds, const Gemm g, const Sched& S, const Epi& E) {
;     ...
;     if constexpr (SP2) {
;         PG8_STAGE(PG8_SB(0, 0), cB, voffB); PG8_STAGE(PG8_SB(0, 1), cB + hstepB, voffB); PG8_STAGE(PG8_SA(0, 0), cA, voffA); PG8_STAGE(PG8_SA(0, 1), cA + hstepA, voffA);
;         if (wr == 1) PG8_BAR;
;         PG8_WAIT_V(2); PG8_BAR;
;         PG8_STAGE(PG8_SB(1, 0), cB + kstep, voffB); PG8_STAGE(PG8_SA(1, 0), cA + kstep, voffA); PG8_STAGE(PG8_SB(1, 1), cB + hstepB + kstep, voffB);
;         PG8_WAIT_V(6); PG8_BAR;
.LBB0_891:
	s_add_u32 s10, s88, 0x110000
	s_addc_u32 s11, s89, 0
	s_lshl_b32 s1, s1, 5
	s_mov_b64 s[12:13], 0x80
	s_and_b32 s16, s1, 0x60
	s_add_i32 m0, s25, 0x18000
	v_lshl_add_u64 v[6:7], v[6:7], 0, s[12:13]
	s_lshl_b32 s5, s0, 13
	s_lshl_b32 s1, s16, 7
	global_load_lds_dwordx4 v[6:7], off
	v_lshl_add_u64 v[4:5], v[4:5], 0, s[12:13]
	s_add_i32 m0, s25, 0x1a000
	s_add_i32 s43, s25, 0x8000
	s_add_i32 s44, s25, 0xa000
	global_load_lds_dwordx4 v[4:5], off
	v_lshl_add_u64 v[0:1], v[0:1], 0, s[12:13]
	s_mov_b32 m0, s43
	s_add_u32 s2, s28, 0x200080
	global_load_lds_dwordx4 v[0:1], off
	v_lshl_add_u64 v[0:1], v[2:3], 0, s[12:13]
	s_mov_b32 m0, s44
	s_addc_u32 s3, s29, 0
	global_load_lds_dwordx4 v[0:1], off
	s_add_i32 m0, s25, 0x1c000
	v_lshl_add_u64 v[0:1], s[2:3], 0, v[128:129]
	global_load_lds_dwordx4 v[0:1], off
	v_lshl_add_u64 v[0:1], s[2:3], 0, v[130:131]
	s_add_i32 m0, s25, 0x1e000
	v_lshlrev_b32_e32 v3, 2, v157
	global_load_lds_dwordx4 v[0:1], off
	s_waitcnt vmcnt(8)
	s_barrier
	v_and_b32_e32 v0, 15, v157
	v_bfe_u32 v1, v157, 4, 2
	v_lshl_or_b32 v144, s0, 6, v0
	v_lshlrev_b32_e32 v2, 4, v1
	v_lshlrev_b32_e32 v4, 6, v157
	s_movk_i32 s0, 0x3c0
	v_lshl_or_b32 v0, v0, 6, v2
	v_and_b32_e32 v3, 32, v3
	v_and_or_b32 v2, v4, s0, v2
	v_bitop3_b32 v145, s1, v2, v3 bitop3:0xf6
	v_cmp_eq_u32_e64 s[0:1], 0, v1
	v_lshl_or_b32 v146, v1, 2, s16
	v_lshlrev_b32_e32 v1, 11, v157
	v_and_b32_e32 v1, 0x1c0000, v1
	v_lshlrev_b32_e32 v2, 14, v10
	v_or3_b32 v1, v8, v1, v2
	v_add_u32_e32 v132, v1, v9
	v_lshlrev_b32_e32 v1, 7, v11
	v_bitop3_b32 v0, v0, s5, v3 bitop3:0xde
	s_waitcnt vmcnt(6)
	s_cmpk_lt_u32 s4, 0x100
	v_and_b32_e32 v1, 0x3c0000, v1
	s_cselect_b64 s[14:15], -1, 0
	v_readlane_b32 s2, v234, 2
	v_or3_b32 v1, v8, v1, v2
	s_add_i32 s47, 0, 0x10000
	s_add_i32 s48, 0, 0x14000
	v_add_u32_e32 v149, 0, v0
	v_mbcnt_lo_u32_b32 v0, -1, 0
	s_ashr_i32 s45, s33, 31
	s_ashr_i32 s46, s2, 31
	v_mov_b32_e32 v133, v129
	v_add_u32_e32 v134, v1, v9
	v_mov_b32_e32 v135, v129
	v_mov_b64_e32 v[136:137], 0x200
	v_mov_b64_e32 v[138:139], 0x1ff
	v_add_u32_e32 v147, s47, v145
	v_add_u32_e32 v148, s48, v145
	v_mbcnt_hi_u32_b32 v150, -1, v0
	s_barrier
	s_branch .LBB0_894
